# stack: hand-written W1 transposes + two-rows-in-flight x-norm loop in phase 0, V^T copy of phase 4 transposed through LDS into 16-byte stores
# baseline (speedup 1.0000x reference)
; __device__ __forceinline__ bf16_t f2bf(float f) { return (bf16_t)(pk2(f, 0.f) & 0xffffu); }
;     __device__ __forceinline__ float* out() const { return (float*)ptr(36); }
;     __device__ __forceinline__ void operator()(const f32x4 (&acc)[2][2][4][2], const Unit& u, int wr, int wc, int fr, int fq) const {
;     ...
;                         if (pn < 6) {
;                             const int vc = c - 1024;
;                             float* vo = smp ? out + O_VS + (size_t)(row - MPR) * 512 + vc : out + O_VP + (size_t)row * 512 + vc;
;                             *(f32x4*)vo = a; *(f32x4*)(vo + 4) = b;
;                             if (!smp) {
;                                 const int bb = row >> 12, t = row & (TP - 1), hh = vc >> 7, dd = vc & 127;
;                                 bf16_t* vt = VT + ((size_t)(bb * 4 + hh) * 128 + dd) * TP + t;
;                                 vt[0] = f2bf(a[0]); vt[TP] = f2bf(a[1]); vt[2 * TP] = f2bf(a[2]); vt[3 * TP] = f2bf(a[3]);
;                                 vt[4 * TP] = f2bf(b[0]); vt[5 * TP] = f2bf(b[1]); vt[6 * TP] = f2bf(b[2]); vt[7 * TP] = f2bf(b[3]);
.LBB0_534:
	v_add_u32_e32 v140, 0xffffc000, v154
	v_lshlrev_b64 v[156:157], 11, v[154:155]
	v_lshlrev_b64 v[176:177], 11, v[140:141]
	s_andn2_b64 vcc, exec, s[72:73]
	v_cndmask_b32_e64 v158, v172, v173, s[10:11]
	v_cndmask_b32_e64 v157, v157, v177, s[10:11]
	v_cndmask_b32_e64 v156, v156, v176, s[10:11]
	s_cbranch_vccnz .LBB0_539
	v_mov_b32_e32 v159, v141
	v_lshl_add_u64 v[176:177], s[18:19], 0, v[158:159]
	v_add_u32_e32 v140, 0xfffffc00, v152
	v_lshl_add_u64 v[176:177], v[176:177], 0, v[156:157]
	v_lshl_add_u64 v[176:177], v[140:141], 2, v[176:177]
	global_store_dwordx4 v[176:177], v[124:127], off
	global_store_dwordx4 v[176:177], v[120:123], off offset:16
	s_and_saveexec_b64 s[72:73], s[8:9]
	s_cbranch_execz .LBB0_537
	v_lshrrev_b32_e32 v140, 7, v140
	v_add_u32_e32 v176, s59, v140
	v_ashrrev_i32_e32 v177, 31, v176
	v_lshlrev_b64 v[176:177], 20, v[176:177]
	v_lshl_add_u64 v[176:177], v[142:143], 0, v[176:177]
	v_lshlrev_b32_e32 v140, 1, v175
	v_lshl_add_u64 v[176:177], v[176:177], 0, v[140:141]
	v_lshrrev_b32_e32 v178, 6, v180
	v_mul_u32_u24_e32 v178, 0x600, v178
	v_add_u32_e32 v178, 0x20000, v178
	v_and_b32_e32 v179, 15, v180
	v_lshl_add_u32 v179, v179, 1, v178
	v_bfe_u32 v140, v180, 4, 2
	v_lshl_add_u32 v179, v140, 8, v179
	v_cvt_pk_bf16_f32 v124, v124, s0
	v_cvt_pk_bf16_f32 v125, v125, s0
	v_cvt_pk_bf16_f32 v126, v126, s0
	v_cvt_pk_bf16_f32 v127, v127, s0
	v_cvt_pk_bf16_f32 v120, v120, s0
	v_cvt_pk_bf16_f32 v121, v121, s0
	v_cvt_pk_bf16_f32 v122, v122, s0
	v_cvt_pk_bf16_f32 v123, v123, s0
	s_nop 0
	ds_write_b16 v179, v124 offset:0
	ds_write_b16 v179, v125 offset:32
	ds_write_b16 v179, v126 offset:64
	ds_write_b16 v179, v127 offset:96
	ds_write_b16 v179, v120 offset:128
	ds_write_b16 v179, v121 offset:160
	ds_write_b16 v179, v122 offset:192
	ds_write_b16 v179, v123 offset:224
	v_and_b32_e32 v140, 63, v180
	v_lshl_add_u32 v178, v140, 4, v178
	v_lshrrev_b32_e32 v179, 1, v140
	s_waitcnt lgkmcnt(0)
	ds_read_b128 v[120:123], v178
	v_lshrrev_b32_e32 v124, 4, v140
	v_lshlrev_b32_e32 v124, 3, v124
	v_sub_u32_e32 v179, v179, v124
	v_lshlrev_b32_e32 v179, 13, v179
	v_and_b32_e32 v124, 1, v140
	v_lshl_add_u32 v179, v124, 4, v179
	v_and_b32_e32 v124, 15, v140
	v_lshlrev_b32_e32 v124, 1, v124
	v_sub_u32_e32 v179, v179, v124
	v_add_co_u32_e32 v176, vcc, v179, v176
	s_nop 1
	v_addc_co_u32_e32 v177, vcc, 0, v177, vcc
	s_waitcnt lgkmcnt(0)
	global_store_dwordx4 v[176:177], v[120:123], off

; __device__ __forceinline__ bf16_t f2bf(float f) { return (bf16_t)(pk2(f, 0.f) & 0xffffu); }
;     __device__ __forceinline__ float* out() const { return (float*)ptr(36); }
;     __device__ __forceinline__ void operator()(const f32x4 (&acc)[2][2][4][2], const Unit& u, int wr, int wc, int fr, int fq) const {
;     ...
;                         if (pn < 6) {
;                             const int vc = c - 1024;
;                             float* vo = smp ? out + O_VS + (size_t)(row - MPR) * 512 + vc : out + O_VP + (size_t)row * 512 + vc;
;                             *(f32x4*)vo = a; *(f32x4*)(vo + 4) = b;
;                             if (!smp) {
;                                 const int bb = row >> 12, t = row & (TP - 1), hh = vc >> 7, dd = vc & 127;
;                                 bf16_t* vt = VT + ((size_t)(bb * 4 + hh) * 128 + dd) * TP + t;
;                                 vt[0] = f2bf(a[0]); vt[TP] = f2bf(a[1]); vt[2 * TP] = f2bf(a[2]); vt[3 * TP] = f2bf(a[3]);
;                                 vt[4 * TP] = f2bf(b[0]); vt[5 * TP] = f2bf(b[1]); vt[6 * TP] = f2bf(b[2]); vt[7 * TP] = f2bf(b[3]);
.LBB0_547:
	v_mov_b32_e32 v159, v141
	v_lshl_add_u64 v[128:129], s[18:19], 0, v[158:159]
	v_add_u32_e32 v140, 0xfffffc80, v152
	v_lshl_add_u64 v[128:129], v[128:129], 0, v[156:157]
	v_lshl_add_u64 v[128:129], v[140:141], 2, v[128:129]
	global_store_dwordx4 v[128:129], v[116:119], off
	global_store_dwordx4 v[128:129], v[112:115], off offset:16
	s_and_saveexec_b64 s[14:15], s[8:9]
	s_cbranch_execz .LBB0_549
	v_lshrrev_b32_e32 v128, 7, v140
	v_add_u32_e32 v128, s59, v128
	v_ashrrev_i32_e32 v129, 31, v128
	v_lshlrev_b64 v[128:129], 20, v[128:129]
	v_lshl_add_u64 v[128:129], v[142:143], 0, v[128:129]
	v_lshlrev_b32_e32 v140, 1, v175
	v_lshl_add_u64 v[128:129], v[128:129], 0, v[140:141]
	v_lshrrev_b32_e32 v130, 6, v180
	v_mul_u32_u24_e32 v130, 0x600, v130
	v_add_u32_e32 v130, 0x20000, v130
	v_and_b32_e32 v131, 15, v180
	v_lshl_add_u32 v131, v131, 1, v130
	v_bfe_u32 v140, v180, 4, 2
	v_lshl_add_u32 v131, v140, 8, v131
	v_cvt_pk_bf16_f32 v116, v116, s0
	v_cvt_pk_bf16_f32 v117, v117, s0
	v_cvt_pk_bf16_f32 v118, v118, s0
	v_cvt_pk_bf16_f32 v119, v119, s0
	v_cvt_pk_bf16_f32 v112, v112, s0
	v_cvt_pk_bf16_f32 v113, v113, s0
	v_cvt_pk_bf16_f32 v114, v114, s0
	v_cvt_pk_bf16_f32 v115, v115, s0
	s_nop 0
	ds_write_b16 v131, v116 offset:0
	ds_write_b16 v131, v117 offset:32
	ds_write_b16 v131, v118 offset:64
	ds_write_b16 v131, v119 offset:96
	ds_write_b16 v131, v112 offset:128
	ds_write_b16 v131, v113 offset:160
	ds_write_b16 v131, v114 offset:192
	ds_write_b16 v131, v115 offset:224
	v_and_b32_e32 v140, 63, v180
	v_lshl_add_u32 v130, v140, 4, v130
	v_lshrrev_b32_e32 v131, 1, v140
	s_waitcnt lgkmcnt(0)
	ds_read_b128 v[112:115], v130
	v_lshrrev_b32_e32 v116, 4, v140
	v_lshlrev_b32_e32 v116, 3, v116
	v_sub_u32_e32 v131, v131, v116
	v_lshlrev_b32_e32 v131, 13, v131
	v_and_b32_e32 v116, 1, v140
	v_lshl_add_u32 v131, v116, 4, v131
	v_and_b32_e32 v116, 15, v140
	v_lshlrev_b32_e32 v116, 1, v116
	v_sub_u32_e32 v131, v131, v116
	v_add_co_u32_e32 v128, vcc, v131, v128
	s_nop 1
	v_addc_co_u32_e32 v129, vcc, 0, v129, vcc
	s_waitcnt lgkmcnt(0)
	global_store_dwordx4 v[128:129], v[112:115], off

; __device__ __forceinline__ bf16_t f2bf(float f) { return (bf16_t)(pk2(f, 0.f) & 0xffffu); }
;     __device__ __forceinline__ float* out() const { return (float*)ptr(36); }
;     __device__ __forceinline__ void operator()(const f32x4 (&acc)[2][2][4][2], const Unit& u, int wr, int wc, int fr, int fq) const {
;     ...
;                         if (pn < 6) {
;                             const int vc = c - 1024;
;                             float* vo = smp ? out + O_VS + (size_t)(row - MPR) * 512 + vc : out + O_VP + (size_t)row * 512 + vc;
;                             *(f32x4*)vo = a; *(f32x4*)(vo + 4) = b;
;                             if (!smp) {
;                                 const int bb = row >> 12, t = row & (TP - 1), hh = vc >> 7, dd = vc & 127;
;                                 bf16_t* vt = VT + ((size_t)(bb * 4 + hh) * 128 + dd) * TP + t;
;                                 vt[0] = f2bf(a[0]); vt[TP] = f2bf(a[1]); vt[2 * TP] = f2bf(a[2]); vt[3 * TP] = f2bf(a[3]);
;                                 vt[4 * TP] = f2bf(b[0]); vt[5 * TP] = f2bf(b[1]); vt[6 * TP] = f2bf(b[2]); vt[7 * TP] = f2bf(b[3]);
.LBB0_570:
	v_add_u32_e32 v140, 0xffffc010, v154
	v_lshlrev_b64 v[118:119], 11, v[116:117]
	v_lshlrev_b64 v[124:125], 11, v[140:141]
	s_andn2_b64 vcc, exec, s[74:75]
	v_cndmask_b32_e64 v120, v172, v173, s[10:11]
	v_cndmask_b32_e64 v119, v119, v125, s[10:11]
	v_cndmask_b32_e64 v118, v118, v124, s[10:11]
	s_cbranch_vccnz .LBB0_575
	v_mov_b32_e32 v121, v141
	v_lshl_add_u64 v[124:125], s[18:19], 0, v[120:121]
	v_add_u32_e32 v140, 0xfffffc00, v152
	v_lshl_add_u64 v[124:125], v[124:125], 0, v[118:119]
	v_lshl_add_u64 v[124:125], v[140:141], 2, v[124:125]
	global_store_dwordx4 v[124:125], v[108:111], off
	global_store_dwordx4 v[124:125], v[104:107], off offset:16
	s_and_saveexec_b64 s[74:75], s[8:9]
	s_cbranch_execz .LBB0_573
	v_lshrrev_b32_e32 v117, 7, v140
	v_add_u32_e32 v124, s59, v117
	v_ashrrev_i32_e32 v125, 31, v124
	v_lshlrev_b64 v[124:125], 20, v[124:125]
	v_lshl_add_u64 v[124:125], v[142:143], 0, v[124:125]
	v_lshlrev_b32_e32 v140, 1, v122
	v_lshl_add_u64 v[124:125], v[124:125], 0, v[140:141]
	v_lshrrev_b32_e32 v126, 6, v180
	v_mul_u32_u24_e32 v126, 0x600, v126
	v_add_u32_e32 v126, 0x20000, v126
	v_and_b32_e32 v127, 15, v180
	v_lshl_add_u32 v127, v127, 1, v126
	v_bfe_u32 v140, v180, 4, 2
	v_lshl_add_u32 v127, v140, 8, v127
	v_cvt_pk_bf16_f32 v108, v108, s0
	v_cvt_pk_bf16_f32 v109, v109, s0
	v_cvt_pk_bf16_f32 v110, v110, s0
	v_cvt_pk_bf16_f32 v111, v111, s0
	v_cvt_pk_bf16_f32 v104, v104, s0
	v_cvt_pk_bf16_f32 v105, v105, s0
	v_cvt_pk_bf16_f32 v106, v106, s0
	v_cvt_pk_bf16_f32 v107, v107, s0
	s_nop 0
	ds_write_b16 v127, v108 offset:0
	ds_write_b16 v127, v109 offset:32
	ds_write_b16 v127, v110 offset:64
	ds_write_b16 v127, v111 offset:96
	ds_write_b16 v127, v104 offset:128
	ds_write_b16 v127, v105 offset:160
	ds_write_b16 v127, v106 offset:192
	ds_write_b16 v127, v107 offset:224
	v_and_b32_e32 v140, 63, v180
	v_lshl_add_u32 v126, v140, 4, v126
	v_lshrrev_b32_e32 v127, 1, v140
	s_waitcnt lgkmcnt(0)
	ds_read_b128 v[104:107], v126
	v_lshrrev_b32_e32 v108, 4, v140
	v_lshlrev_b32_e32 v108, 3, v108
	v_sub_u32_e32 v127, v127, v108
	v_lshlrev_b32_e32 v127, 13, v127
	v_and_b32_e32 v108, 1, v140
	v_lshl_add_u32 v127, v108, 4, v127
	v_and_b32_e32 v108, 15, v140
	v_lshlrev_b32_e32 v108, 1, v108
	v_sub_u32_e32 v127, v127, v108
	v_add_co_u32_e32 v124, vcc, v127, v124
	s_nop 1
	v_addc_co_u32_e32 v125, vcc, 0, v125, vcc
	s_waitcnt lgkmcnt(0)
	global_store_dwordx4 v[124:125], v[104:107], off

; __device__ __forceinline__ bf16_t f2bf(float f) { return (bf16_t)(pk2(f, 0.f) & 0xffffu); }
;     __device__ __forceinline__ float* out() const { return (float*)ptr(36); }
;     __device__ __forceinline__ void operator()(const f32x4 (&acc)[2][2][4][2], const Unit& u, int wr, int wc, int fr, int fq) const {
;     ...
;                         if (pn < 6) {
;                             const int vc = c - 1024;
;                             float* vo = smp ? out + O_VS + (size_t)(row - MPR) * 512 + vc : out + O_VP + (size_t)row * 512 + vc;
;                             *(f32x4*)vo = a; *(f32x4*)(vo + 4) = b;
;                             if (!smp) {
;                                 const int bb = row >> 12, t = row & (TP - 1), hh = vc >> 7, dd = vc & 127;
;                                 bf16_t* vt = VT + ((size_t)(bb * 4 + hh) * 128 + dd) * TP + t;
;                                 vt[0] = f2bf(a[0]); vt[TP] = f2bf(a[1]); vt[2 * TP] = f2bf(a[2]); vt[3 * TP] = f2bf(a[3]);
;                                 vt[4 * TP] = f2bf(b[0]); vt[5 * TP] = f2bf(b[1]); vt[6 * TP] = f2bf(b[2]); vt[7 * TP] = f2bf(b[3]);
.LBB0_583:
	v_mov_b32_e32 v121, v141
	v_lshl_add_u64 v[112:113], s[18:19], 0, v[120:121]
	v_add_u32_e32 v140, 0xfffffc80, v152
	v_lshl_add_u64 v[112:113], v[112:113], 0, v[118:119]
	v_lshl_add_u64 v[112:113], v[140:141], 2, v[112:113]
	global_store_dwordx4 v[112:113], v[100:103], off
	global_store_dwordx4 v[112:113], v[96:99], off offset:16
	s_and_saveexec_b64 s[12:13], s[8:9]
	s_cbranch_execz .LBB0_585
	v_lshrrev_b32_e32 v112, 7, v140
	v_add_u32_e32 v112, s59, v112
	v_ashrrev_i32_e32 v113, 31, v112
	v_lshlrev_b64 v[112:113], 20, v[112:113]
	v_lshl_add_u64 v[112:113], v[142:143], 0, v[112:113]
	v_lshlrev_b32_e32 v140, 1, v122
	v_lshl_add_u64 v[112:113], v[112:113], 0, v[140:141]
	v_lshrrev_b32_e32 v114, 6, v180
	v_mul_u32_u24_e32 v114, 0x600, v114
	v_add_u32_e32 v114, 0x20000, v114
	v_and_b32_e32 v115, 15, v180
	v_lshl_add_u32 v115, v115, 1, v114
	v_bfe_u32 v140, v180, 4, 2
	v_lshl_add_u32 v115, v140, 8, v115
	v_cvt_pk_bf16_f32 v100, v100, s0
	v_cvt_pk_bf16_f32 v101, v101, s0
	v_cvt_pk_bf16_f32 v102, v102, s0
	v_cvt_pk_bf16_f32 v103, v103, s0
	v_cvt_pk_bf16_f32 v96, v96, s0
	v_cvt_pk_bf16_f32 v97, v97, s0
	v_cvt_pk_bf16_f32 v98, v98, s0
	v_cvt_pk_bf16_f32 v99, v99, s0
	s_nop 0
	ds_write_b16 v115, v100 offset:0
	ds_write_b16 v115, v101 offset:32
	ds_write_b16 v115, v102 offset:64
	ds_write_b16 v115, v103 offset:96
	ds_write_b16 v115, v96 offset:128
	ds_write_b16 v115, v97 offset:160
	ds_write_b16 v115, v98 offset:192
	ds_write_b16 v115, v99 offset:224
	v_and_b32_e32 v140, 63, v180
	v_lshl_add_u32 v114, v140, 4, v114
	v_lshrrev_b32_e32 v115, 1, v140
	s_waitcnt lgkmcnt(0)
	ds_read_b128 v[96:99], v114
	v_lshrrev_b32_e32 v100, 4, v140
	v_lshlrev_b32_e32 v100, 3, v100
	v_sub_u32_e32 v115, v115, v100
	v_lshlrev_b32_e32 v115, 13, v115
	v_and_b32_e32 v100, 1, v140
	v_lshl_add_u32 v115, v100, 4, v115
	v_and_b32_e32 v100, 15, v140
	v_lshlrev_b32_e32 v100, 1, v100
	v_sub_u32_e32 v115, v115, v100
	v_add_co_u32_e32 v112, vcc, v115, v112
	s_nop 1
	v_addc_co_u32_e32 v113, vcc, 0, v113, vcc
	s_waitcnt lgkmcnt(0)
	global_store_dwordx4 v[112:113], v[96:99], off

; __device__ __forceinline__ bf16_t f2bf(float f) { return (bf16_t)(pk2(f, 0.f) & 0xffffu); }
;     __device__ __forceinline__ float* out() const { return (float*)ptr(36); }
;     __device__ __forceinline__ void operator()(const f32x4 (&acc)[2][2][4][2], const Unit& u, int wr, int wc, int fr, int fq) const {
;     ...
;                         if (pn < 6) {
;                             const int vc = c - 1024;
;                             float* vo = smp ? out + O_VS + (size_t)(row - MPR) * 512 + vc : out + O_VP + (size_t)row * 512 + vc;
;                             *(f32x4*)vo = a; *(f32x4*)(vo + 4) = b;
;                             if (!smp) {
;                                 const int bb = row >> 12, t = row & (TP - 1), hh = vc >> 7, dd = vc & 127;
;                                 bf16_t* vt = VT + ((size_t)(bb * 4 + hh) * 128 + dd) * TP + t;
;                                 vt[0] = f2bf(a[0]); vt[TP] = f2bf(a[1]); vt[2 * TP] = f2bf(a[2]); vt[3 * TP] = f2bf(a[3]);
;                                 vt[4 * TP] = f2bf(b[0]); vt[5 * TP] = f2bf(b[1]); vt[6 * TP] = f2bf(b[2]); vt[7 * TP] = f2bf(b[3]);
.LBB0_606:
	v_add_u32_e32 v140, 0xffffc020, v154
	v_lshlrev_b64 v[102:103], 11, v[100:101]
	v_lshlrev_b64 v[108:109], 11, v[140:141]
	s_andn2_b64 vcc, exec, s[74:75]
	v_cndmask_b32_e64 v104, v172, v173, s[10:11]
	v_cndmask_b32_e64 v103, v103, v109, s[10:11]
	v_cndmask_b32_e64 v102, v102, v108, s[10:11]
	s_cbranch_vccnz .LBB0_611
	v_mov_b32_e32 v105, v141
	v_lshl_add_u64 v[108:109], s[18:19], 0, v[104:105]
	v_add_u32_e32 v140, 0xfffffc00, v152
	v_lshl_add_u64 v[108:109], v[108:109], 0, v[102:103]
	v_lshl_add_u64 v[108:109], v[140:141], 2, v[108:109]
	global_store_dwordx4 v[108:109], v[92:95], off
	global_store_dwordx4 v[108:109], v[88:91], off offset:16
	s_and_saveexec_b64 s[74:75], s[8:9]
	s_cbranch_execz .LBB0_609
	v_lshrrev_b32_e32 v101, 7, v140
	v_add_u32_e32 v108, s59, v101
	v_ashrrev_i32_e32 v109, 31, v108
	v_lshlrev_b64 v[108:109], 20, v[108:109]
	v_lshl_add_u64 v[108:109], v[142:143], 0, v[108:109]
	v_lshlrev_b32_e32 v140, 1, v106
	v_lshl_add_u64 v[108:109], v[108:109], 0, v[140:141]
	v_lshrrev_b32_e32 v110, 6, v180
	v_mul_u32_u24_e32 v110, 0x600, v110
	v_add_u32_e32 v110, 0x20000, v110
	v_and_b32_e32 v111, 15, v180
	v_lshl_add_u32 v111, v111, 1, v110
	v_bfe_u32 v140, v180, 4, 2
	v_lshl_add_u32 v111, v140, 8, v111
	v_cvt_pk_bf16_f32 v92, v92, s0
	v_cvt_pk_bf16_f32 v93, v93, s0
	v_cvt_pk_bf16_f32 v94, v94, s0
	v_cvt_pk_bf16_f32 v95, v95, s0
	v_cvt_pk_bf16_f32 v88, v88, s0
	v_cvt_pk_bf16_f32 v89, v89, s0
	v_cvt_pk_bf16_f32 v90, v90, s0
	v_cvt_pk_bf16_f32 v91, v91, s0
	s_nop 0
	ds_write_b16 v111, v92 offset:0
	ds_write_b16 v111, v93 offset:32
	ds_write_b16 v111, v94 offset:64
	ds_write_b16 v111, v95 offset:96
	ds_write_b16 v111, v88 offset:128
	ds_write_b16 v111, v89 offset:160
	ds_write_b16 v111, v90 offset:192
	ds_write_b16 v111, v91 offset:224
	v_and_b32_e32 v140, 63, v180
	v_lshl_add_u32 v110, v140, 4, v110
	v_lshrrev_b32_e32 v111, 1, v140
	s_waitcnt lgkmcnt(0)
	ds_read_b128 v[88:91], v110
	v_lshrrev_b32_e32 v92, 4, v140
	v_lshlrev_b32_e32 v92, 3, v92
	v_sub_u32_e32 v111, v111, v92
	v_lshlrev_b32_e32 v111, 13, v111
	v_and_b32_e32 v92, 1, v140
	v_lshl_add_u32 v111, v92, 4, v111
	v_and_b32_e32 v92, 15, v140
	v_lshlrev_b32_e32 v92, 1, v92
	v_sub_u32_e32 v111, v111, v92
	v_add_co_u32_e32 v108, vcc, v111, v108
	s_nop 1
	v_addc_co_u32_e32 v109, vcc, 0, v109, vcc
	s_waitcnt lgkmcnt(0)
	global_store_dwordx4 v[108:109], v[88:91], off

; __device__ __forceinline__ bf16_t f2bf(float f) { return (bf16_t)(pk2(f, 0.f) & 0xffffu); }
;     __device__ __forceinline__ float* out() const { return (float*)ptr(36); }
;     __device__ __forceinline__ void operator()(const f32x4 (&acc)[2][2][4][2], const Unit& u, int wr, int wc, int fr, int fq) const {
;     ...
;                         if (pn < 6) {
;                             const int vc = c - 1024;
;                             float* vo = smp ? out + O_VS + (size_t)(row - MPR) * 512 + vc : out + O_VP + (size_t)row * 512 + vc;
;                             *(f32x4*)vo = a; *(f32x4*)(vo + 4) = b;
;                             if (!smp) {
;                                 const int bb = row >> 12, t = row & (TP - 1), hh = vc >> 7, dd = vc & 127;
;                                 bf16_t* vt = VT + ((size_t)(bb * 4 + hh) * 128 + dd) * TP + t;
;                                 vt[0] = f2bf(a[0]); vt[TP] = f2bf(a[1]); vt[2 * TP] = f2bf(a[2]); vt[3 * TP] = f2bf(a[3]);
;                                 vt[4 * TP] = f2bf(b[0]); vt[5 * TP] = f2bf(b[1]); vt[6 * TP] = f2bf(b[2]); vt[7 * TP] = f2bf(b[3]);
.LBB0_619:
	v_mov_b32_e32 v105, v141
	v_lshl_add_u64 v[96:97], s[18:19], 0, v[104:105]
	v_add_u32_e32 v140, 0xfffffc80, v152
	v_lshl_add_u64 v[96:97], v[96:97], 0, v[102:103]
	v_lshl_add_u64 v[96:97], v[140:141], 2, v[96:97]
	global_store_dwordx4 v[96:97], v[84:87], off
	global_store_dwordx4 v[96:97], v[80:83], off offset:16
	s_and_saveexec_b64 s[12:13], s[8:9]
	s_cbranch_execz .LBB0_621
	v_lshrrev_b32_e32 v96, 7, v140
	v_add_u32_e32 v96, s59, v96
	v_ashrrev_i32_e32 v97, 31, v96
	v_lshlrev_b64 v[96:97], 20, v[96:97]
	v_lshl_add_u64 v[96:97], v[142:143], 0, v[96:97]
	v_lshlrev_b32_e32 v140, 1, v106
	v_lshl_add_u64 v[96:97], v[96:97], 0, v[140:141]
	v_lshrrev_b32_e32 v98, 6, v180
	v_mul_u32_u24_e32 v98, 0x600, v98
	v_add_u32_e32 v98, 0x20000, v98
	v_and_b32_e32 v99, 15, v180
	v_lshl_add_u32 v99, v99, 1, v98
	v_bfe_u32 v140, v180, 4, 2
	v_lshl_add_u32 v99, v140, 8, v99
	v_cvt_pk_bf16_f32 v84, v84, s0
	v_cvt_pk_bf16_f32 v85, v85, s0
	v_cvt_pk_bf16_f32 v86, v86, s0
	v_cvt_pk_bf16_f32 v87, v87, s0
	v_cvt_pk_bf16_f32 v80, v80, s0
	v_cvt_pk_bf16_f32 v81, v81, s0
	v_cvt_pk_bf16_f32 v82, v82, s0
	v_cvt_pk_bf16_f32 v83, v83, s0
	s_nop 0
	ds_write_b16 v99, v84 offset:0
	ds_write_b16 v99, v85 offset:32
	ds_write_b16 v99, v86 offset:64
	ds_write_b16 v99, v87 offset:96
	ds_write_b16 v99, v80 offset:128
	ds_write_b16 v99, v81 offset:160
	ds_write_b16 v99, v82 offset:192
	ds_write_b16 v99, v83 offset:224
	v_and_b32_e32 v140, 63, v180
	v_lshl_add_u32 v98, v140, 4, v98
	v_lshrrev_b32_e32 v99, 1, v140
	s_waitcnt lgkmcnt(0)
	ds_read_b128 v[80:83], v98
	v_lshrrev_b32_e32 v84, 4, v140
	v_lshlrev_b32_e32 v84, 3, v84
	v_sub_u32_e32 v99, v99, v84
	v_lshlrev_b32_e32 v99, 13, v99
	v_and_b32_e32 v84, 1, v140
	v_lshl_add_u32 v99, v84, 4, v99
	v_and_b32_e32 v84, 15, v140
	v_lshlrev_b32_e32 v84, 1, v84
	v_sub_u32_e32 v99, v99, v84
	v_add_co_u32_e32 v96, vcc, v99, v96
	s_nop 1
	v_addc_co_u32_e32 v97, vcc, 0, v97, vcc
	s_waitcnt lgkmcnt(0)
	global_store_dwordx4 v[96:97], v[80:83], off

; __device__ __forceinline__ bf16_t f2bf(float f) { return (bf16_t)(pk2(f, 0.f) & 0xffffu); }
;     __device__ __forceinline__ float* out() const { return (float*)ptr(36); }
;     __device__ __forceinline__ void operator()(const f32x4 (&acc)[2][2][4][2], const Unit& u, int wr, int wc, int fr, int fq) const {
;     ...
;                         if (pn < 6) {
;                             const int vc = c - 1024;
;                             float* vo = smp ? out + O_VS + (size_t)(row - MPR) * 512 + vc : out + O_VP + (size_t)row * 512 + vc;
;                             *(f32x4*)vo = a; *(f32x4*)(vo + 4) = b;
;                             if (!smp) {
;                                 const int bb = row >> 12, t = row & (TP - 1), hh = vc >> 7, dd = vc & 127;
;                                 bf16_t* vt = VT + ((size_t)(bb * 4 + hh) * 128 + dd) * TP + t;
;                                 vt[0] = f2bf(a[0]); vt[TP] = f2bf(a[1]); vt[2 * TP] = f2bf(a[2]); vt[3 * TP] = f2bf(a[3]);
;                                 vt[4 * TP] = f2bf(b[0]); vt[5 * TP] = f2bf(b[1]); vt[6 * TP] = f2bf(b[2]); vt[7 * TP] = f2bf(b[3]);
.LBB0_642:
	v_add_u32_e32 v140, 0xffffc030, v154
	v_lshlrev_b64 v[86:87], 11, v[84:85]
	v_lshlrev_b64 v[92:93], 11, v[140:141]
	s_andn2_b64 vcc, exec, s[76:77]
	v_cndmask_b32_e64 v88, v172, v173, s[10:11]
	v_cndmask_b32_e64 v87, v87, v93, s[10:11]
	v_cndmask_b32_e64 v86, v86, v92, s[10:11]
	s_cbranch_vccnz .LBB0_647
	v_mov_b32_e32 v89, v141
	v_lshl_add_u64 v[92:93], s[18:19], 0, v[88:89]
	v_add_u32_e32 v140, 0xfffffc00, v152
	v_lshl_add_u64 v[92:93], v[92:93], 0, v[86:87]
	v_lshl_add_u64 v[92:93], v[140:141], 2, v[92:93]
	global_store_dwordx4 v[92:93], v[76:79], off
	global_store_dwordx4 v[92:93], v[72:75], off offset:16
	s_and_saveexec_b64 s[76:77], s[8:9]
	s_cbranch_execz .LBB0_645
	v_lshrrev_b32_e32 v85, 7, v140
	v_add_u32_e32 v92, s59, v85
	v_ashrrev_i32_e32 v93, 31, v92
	v_lshlrev_b64 v[92:93], 20, v[92:93]
	v_lshl_add_u64 v[92:93], v[142:143], 0, v[92:93]
	v_lshlrev_b32_e32 v140, 1, v90
	v_lshl_add_u64 v[92:93], v[92:93], 0, v[140:141]
	v_lshrrev_b32_e32 v94, 6, v180
	v_mul_u32_u24_e32 v94, 0x600, v94
	v_add_u32_e32 v94, 0x20000, v94
	v_and_b32_e32 v95, 15, v180
	v_lshl_add_u32 v95, v95, 1, v94
	v_bfe_u32 v140, v180, 4, 2
	v_lshl_add_u32 v95, v140, 8, v95
	v_cvt_pk_bf16_f32 v76, v76, s0
	v_cvt_pk_bf16_f32 v77, v77, s0
	v_cvt_pk_bf16_f32 v78, v78, s0
	v_cvt_pk_bf16_f32 v79, v79, s0
	v_cvt_pk_bf16_f32 v72, v72, s0
	v_cvt_pk_bf16_f32 v73, v73, s0
	v_cvt_pk_bf16_f32 v74, v74, s0
	v_cvt_pk_bf16_f32 v75, v75, s0
	s_nop 0
	ds_write_b16 v95, v76 offset:0
	ds_write_b16 v95, v77 offset:32
	ds_write_b16 v95, v78 offset:64
	ds_write_b16 v95, v79 offset:96
	ds_write_b16 v95, v72 offset:128
	ds_write_b16 v95, v73 offset:160
	ds_write_b16 v95, v74 offset:192
	ds_write_b16 v95, v75 offset:224
	v_and_b32_e32 v140, 63, v180
	v_lshl_add_u32 v94, v140, 4, v94
	v_lshrrev_b32_e32 v95, 1, v140
	s_waitcnt lgkmcnt(0)
	ds_read_b128 v[72:75], v94
	v_lshrrev_b32_e32 v76, 4, v140
	v_lshlrev_b32_e32 v76, 3, v76
	v_sub_u32_e32 v95, v95, v76
	v_lshlrev_b32_e32 v95, 13, v95
	v_and_b32_e32 v76, 1, v140
	v_lshl_add_u32 v95, v76, 4, v95
	v_and_b32_e32 v76, 15, v140
	v_lshlrev_b32_e32 v76, 1, v76
	v_sub_u32_e32 v95, v95, v76
	v_add_co_u32_e32 v92, vcc, v95, v92
	s_nop 1
	v_addc_co_u32_e32 v93, vcc, 0, v93, vcc
	s_waitcnt lgkmcnt(0)
	global_store_dwordx4 v[92:93], v[72:75], off

; __device__ __forceinline__ bf16_t f2bf(float f) { return (bf16_t)(pk2(f, 0.f) & 0xffffu); }
;     __device__ __forceinline__ float* out() const { return (float*)ptr(36); }
;     __device__ __forceinline__ void operator()(const f32x4 (&acc)[2][2][4][2], const Unit& u, int wr, int wc, int fr, int fq) const {
;     ...
;                         if (pn < 6) {
;                             const int vc = c - 1024;
;                             float* vo = smp ? out + O_VS + (size_t)(row - MPR) * 512 + vc : out + O_VP + (size_t)row * 512 + vc;
;                             *(f32x4*)vo = a; *(f32x4*)(vo + 4) = b;
;                             if (!smp) {
;                                 const int bb = row >> 12, t = row & (TP - 1), hh = vc >> 7, dd = vc & 127;
;                                 bf16_t* vt = VT + ((size_t)(bb * 4 + hh) * 128 + dd) * TP + t;
;                                 vt[0] = f2bf(a[0]); vt[TP] = f2bf(a[1]); vt[2 * TP] = f2bf(a[2]); vt[3 * TP] = f2bf(a[3]);
;                                 vt[4 * TP] = f2bf(b[0]); vt[5 * TP] = f2bf(b[1]); vt[6 * TP] = f2bf(b[2]); vt[7 * TP] = f2bf(b[3]);
.LBB0_655:
	v_mov_b32_e32 v89, v141
	v_lshl_add_u64 v[80:81], s[18:19], 0, v[88:89]
	v_add_u32_e32 v140, 0xfffffc80, v152
	v_lshl_add_u64 v[80:81], v[80:81], 0, v[86:87]
	v_lshl_add_u64 v[80:81], v[140:141], 2, v[80:81]
	global_store_dwordx4 v[80:81], v[68:71], off
	global_store_dwordx4 v[80:81], v[64:67], off offset:16
	s_and_saveexec_b64 s[12:13], s[8:9]
	s_cbranch_execz .LBB0_657
	v_lshrrev_b32_e32 v80, 7, v140
	v_add_u32_e32 v80, s59, v80
	v_ashrrev_i32_e32 v81, 31, v80
	v_lshlrev_b64 v[80:81], 20, v[80:81]
	v_lshl_add_u64 v[80:81], v[142:143], 0, v[80:81]
	v_lshlrev_b32_e32 v140, 1, v90
	v_lshl_add_u64 v[80:81], v[80:81], 0, v[140:141]
	v_lshrrev_b32_e32 v82, 6, v180
	v_mul_u32_u24_e32 v82, 0x600, v82
	v_add_u32_e32 v82, 0x20000, v82
	v_and_b32_e32 v83, 15, v180
	v_lshl_add_u32 v83, v83, 1, v82
	v_bfe_u32 v140, v180, 4, 2
	v_lshl_add_u32 v83, v140, 8, v83
	v_cvt_pk_bf16_f32 v68, v68, s0
	v_cvt_pk_bf16_f32 v69, v69, s0
	v_cvt_pk_bf16_f32 v70, v70, s0
	v_cvt_pk_bf16_f32 v71, v71, s0
	v_cvt_pk_bf16_f32 v64, v64, s0
	v_cvt_pk_bf16_f32 v65, v65, s0
	v_cvt_pk_bf16_f32 v66, v66, s0
	v_cvt_pk_bf16_f32 v67, v67, s0
	s_nop 0
	ds_write_b16 v83, v68 offset:0
	ds_write_b16 v83, v69 offset:32
	ds_write_b16 v83, v70 offset:64
	ds_write_b16 v83, v71 offset:96
	ds_write_b16 v83, v64 offset:128
	ds_write_b16 v83, v65 offset:160
	ds_write_b16 v83, v66 offset:192
	ds_write_b16 v83, v67 offset:224
	v_and_b32_e32 v140, 63, v180
	v_lshl_add_u32 v82, v140, 4, v82
	v_lshrrev_b32_e32 v83, 1, v140
	s_waitcnt lgkmcnt(0)
	ds_read_b128 v[64:67], v82
	v_lshrrev_b32_e32 v68, 4, v140
	v_lshlrev_b32_e32 v68, 3, v68
	v_sub_u32_e32 v83, v83, v68
	v_lshlrev_b32_e32 v83, 13, v83
	v_and_b32_e32 v68, 1, v140
	v_lshl_add_u32 v83, v68, 4, v83
	v_and_b32_e32 v68, 15, v140
	v_lshlrev_b32_e32 v68, 1, v68
	v_sub_u32_e32 v83, v83, v68
	v_add_co_u32_e32 v80, vcc, v83, v80
	s_nop 1
	v_addc_co_u32_e32 v81, vcc, 0, v81, vcc
	s_waitcnt lgkmcnt(0)
	global_store_dwordx4 v[80:81], v[64:67], off

; __device__ __forceinline__ bf16_t f2bf(float f) { return (bf16_t)(pk2(f, 0.f) & 0xffffu); }
;     __device__ __forceinline__ float* out() const { return (float*)ptr(36); }
;     __device__ __forceinline__ void operator()(const f32x4 (&acc)[2][2][4][2], const Unit& u, int wr, int wc, int fr, int fq) const {
;     ...
;                         if (pn < 6) {
;                             const int vc = c - 1024;
;                             float* vo = smp ? out + O_VS + (size_t)(row - MPR) * 512 + vc : out + O_VP + (size_t)row * 512 + vc;
;                             *(f32x4*)vo = a; *(f32x4*)(vo + 4) = b;
;                             if (!smp) {
;                                 const int bb = row >> 12, t = row & (TP - 1), hh = vc >> 7, dd = vc & 127;
;                                 bf16_t* vt = VT + ((size_t)(bb * 4 + hh) * 128 + dd) * TP + t;
;                                 vt[0] = f2bf(a[0]); vt[TP] = f2bf(a[1]); vt[2 * TP] = f2bf(a[2]); vt[3 * TP] = f2bf(a[3]);
;                                 vt[4 * TP] = f2bf(b[0]); vt[5 * TP] = f2bf(b[1]); vt[6 * TP] = f2bf(b[2]); vt[7 * TP] = f2bf(b[3]);
.LBB0_678:
	v_add_u32_e32 v140, 0xffffc000, v68
	v_lshlrev_b64 v[70:71], 11, v[68:69]
	v_lshlrev_b64 v[76:77], 11, v[140:141]
	s_andn2_b64 vcc, exec, s[74:75]
	v_cndmask_b32_e64 v72, v172, v173, s[10:11]
	v_cndmask_b32_e64 v71, v71, v77, s[10:11]
	v_cndmask_b32_e64 v70, v70, v76, s[10:11]
	s_cbranch_vccnz .LBB0_683
	v_mov_b32_e32 v73, v141
	v_lshl_add_u64 v[76:77], s[18:19], 0, v[72:73]
	v_add_u32_e32 v140, 0xfffffc00, v152
	v_lshl_add_u64 v[76:77], v[76:77], 0, v[70:71]
	v_lshl_add_u64 v[76:77], v[140:141], 2, v[76:77]
	global_store_dwordx4 v[76:77], v[60:63], off
	global_store_dwordx4 v[76:77], v[56:59], off offset:16
	s_and_saveexec_b64 s[74:75], s[8:9]
	s_cbranch_execz .LBB0_681
	v_lshrrev_b32_e32 v69, 7, v140
	v_add_u32_e32 v76, s59, v69
	v_ashrrev_i32_e32 v77, 31, v76
	v_lshlrev_b64 v[76:77], 20, v[76:77]
	v_lshl_add_u64 v[76:77], v[142:143], 0, v[76:77]
	v_lshlrev_b32_e32 v140, 1, v74
	v_lshl_add_u64 v[76:77], v[76:77], 0, v[140:141]
	v_lshrrev_b32_e32 v78, 6, v180
	v_mul_u32_u24_e32 v78, 0x600, v78
	v_add_u32_e32 v78, 0x20000, v78
	v_and_b32_e32 v79, 15, v180
	v_lshl_add_u32 v79, v79, 1, v78
	v_bfe_u32 v140, v180, 4, 2
	v_lshl_add_u32 v79, v140, 8, v79
	v_cvt_pk_bf16_f32 v60, v60, s0
	v_cvt_pk_bf16_f32 v61, v61, s0
	v_cvt_pk_bf16_f32 v62, v62, s0
	v_cvt_pk_bf16_f32 v63, v63, s0
	v_cvt_pk_bf16_f32 v56, v56, s0
	v_cvt_pk_bf16_f32 v57, v57, s0
	v_cvt_pk_bf16_f32 v58, v58, s0
	v_cvt_pk_bf16_f32 v59, v59, s0
	s_nop 0
	ds_write_b16 v79, v60 offset:0
	ds_write_b16 v79, v61 offset:32
	ds_write_b16 v79, v62 offset:64
	ds_write_b16 v79, v63 offset:96
	ds_write_b16 v79, v56 offset:128
	ds_write_b16 v79, v57 offset:160
	ds_write_b16 v79, v58 offset:192
	ds_write_b16 v79, v59 offset:224
	v_and_b32_e32 v140, 63, v180
	v_lshl_add_u32 v78, v140, 4, v78
	v_lshrrev_b32_e32 v79, 1, v140
	s_waitcnt lgkmcnt(0)
	ds_read_b128 v[56:59], v78
	v_lshrrev_b32_e32 v60, 4, v140
	v_lshlrev_b32_e32 v60, 3, v60
	v_sub_u32_e32 v79, v79, v60
	v_lshlrev_b32_e32 v79, 13, v79
	v_and_b32_e32 v60, 1, v140
	v_lshl_add_u32 v79, v60, 4, v79
	v_and_b32_e32 v60, 15, v140
	v_lshlrev_b32_e32 v60, 1, v60
	v_sub_u32_e32 v79, v79, v60
	v_add_co_u32_e32 v76, vcc, v79, v76
	s_nop 1
	v_addc_co_u32_e32 v77, vcc, 0, v77, vcc
	s_waitcnt lgkmcnt(0)
	global_store_dwordx4 v[76:77], v[56:59], off

; __device__ __forceinline__ bf16_t f2bf(float f) { return (bf16_t)(pk2(f, 0.f) & 0xffffu); }
;     __device__ __forceinline__ float* out() const { return (float*)ptr(36); }
;     __device__ __forceinline__ void operator()(const f32x4 (&acc)[2][2][4][2], const Unit& u, int wr, int wc, int fr, int fq) const {
;     ...
;                         if (pn < 6) {
;                             const int vc = c - 1024;
;                             float* vo = smp ? out + O_VS + (size_t)(row - MPR) * 512 + vc : out + O_VP + (size_t)row * 512 + vc;
;                             *(f32x4*)vo = a; *(f32x4*)(vo + 4) = b;
;                             if (!smp) {
;                                 const int bb = row >> 12, t = row & (TP - 1), hh = vc >> 7, dd = vc & 127;
;                                 bf16_t* vt = VT + ((size_t)(bb * 4 + hh) * 128 + dd) * TP + t;
;                                 vt[0] = f2bf(a[0]); vt[TP] = f2bf(a[1]); vt[2 * TP] = f2bf(a[2]); vt[3 * TP] = f2bf(a[3]);
;                                 vt[4 * TP] = f2bf(b[0]); vt[5 * TP] = f2bf(b[1]); vt[6 * TP] = f2bf(b[2]); vt[7 * TP] = f2bf(b[3]);
.LBB0_691:
	v_mov_b32_e32 v73, v141
	v_lshl_add_u64 v[64:65], s[18:19], 0, v[72:73]
	v_add_u32_e32 v140, 0xfffffc80, v152
	v_lshl_add_u64 v[64:65], v[64:65], 0, v[70:71]
	v_lshl_add_u64 v[64:65], v[140:141], 2, v[64:65]
	global_store_dwordx4 v[64:65], v[52:55], off
	global_store_dwordx4 v[64:65], v[48:51], off offset:16
	s_and_saveexec_b64 s[12:13], s[8:9]
	s_cbranch_execz .LBB0_693
	v_lshrrev_b32_e32 v64, 7, v140
	v_add_u32_e32 v64, s59, v64
	v_ashrrev_i32_e32 v65, 31, v64
	v_lshlrev_b64 v[64:65], 20, v[64:65]
	v_lshl_add_u64 v[64:65], v[142:143], 0, v[64:65]
	v_lshlrev_b32_e32 v140, 1, v74
	v_lshl_add_u64 v[64:65], v[64:65], 0, v[140:141]
	v_lshrrev_b32_e32 v66, 6, v180
	v_mul_u32_u24_e32 v66, 0x600, v66
	v_add_u32_e32 v66, 0x20000, v66
	v_and_b32_e32 v67, 15, v180
	v_lshl_add_u32 v67, v67, 1, v66
	v_bfe_u32 v140, v180, 4, 2
	v_lshl_add_u32 v67, v140, 8, v67
	v_cvt_pk_bf16_f32 v52, v52, s0
	v_cvt_pk_bf16_f32 v53, v53, s0
	v_cvt_pk_bf16_f32 v54, v54, s0
	v_cvt_pk_bf16_f32 v55, v55, s0
	v_cvt_pk_bf16_f32 v48, v48, s0
	v_cvt_pk_bf16_f32 v49, v49, s0
	v_cvt_pk_bf16_f32 v50, v50, s0
	v_cvt_pk_bf16_f32 v51, v51, s0
	s_nop 0
	ds_write_b16 v67, v52 offset:0
	ds_write_b16 v67, v53 offset:32
	ds_write_b16 v67, v54 offset:64
	ds_write_b16 v67, v55 offset:96
	ds_write_b16 v67, v48 offset:128
	ds_write_b16 v67, v49 offset:160
	ds_write_b16 v67, v50 offset:192
	ds_write_b16 v67, v51 offset:224
	v_and_b32_e32 v140, 63, v180
	v_lshl_add_u32 v66, v140, 4, v66
	v_lshrrev_b32_e32 v67, 1, v140
	s_waitcnt lgkmcnt(0)
	ds_read_b128 v[48:51], v66
	v_lshrrev_b32_e32 v52, 4, v140
	v_lshlrev_b32_e32 v52, 3, v52
	v_sub_u32_e32 v67, v67, v52
	v_lshlrev_b32_e32 v67, 13, v67
	v_and_b32_e32 v52, 1, v140
	v_lshl_add_u32 v67, v52, 4, v67
	v_and_b32_e32 v52, 15, v140
	v_lshlrev_b32_e32 v52, 1, v52
	v_sub_u32_e32 v67, v67, v52
	v_add_co_u32_e32 v64, vcc, v67, v64
	s_nop 1
	v_addc_co_u32_e32 v65, vcc, 0, v65, vcc
	s_waitcnt lgkmcnt(0)
	global_store_dwordx4 v[64:65], v[48:51], off

; __device__ __forceinline__ bf16_t f2bf(float f) { return (bf16_t)(pk2(f, 0.f) & 0xffffu); }
;     __device__ __forceinline__ float* out() const { return (float*)ptr(36); }
;     __device__ __forceinline__ void operator()(const f32x4 (&acc)[2][2][4][2], const Unit& u, int wr, int wc, int fr, int fq) const {
;     ...
;                         if (pn < 6) {
;                             const int vc = c - 1024;
;                             float* vo = smp ? out + O_VS + (size_t)(row - MPR) * 512 + vc : out + O_VP + (size_t)row * 512 + vc;
;                             *(f32x4*)vo = a; *(f32x4*)(vo + 4) = b;
;                             if (!smp) {
;                                 const int bb = row >> 12, t = row & (TP - 1), hh = vc >> 7, dd = vc & 127;
;                                 bf16_t* vt = VT + ((size_t)(bb * 4 + hh) * 128 + dd) * TP + t;
;                                 vt[0] = f2bf(a[0]); vt[TP] = f2bf(a[1]); vt[2 * TP] = f2bf(a[2]); vt[3 * TP] = f2bf(a[3]);
;                                 vt[4 * TP] = f2bf(b[0]); vt[5 * TP] = f2bf(b[1]); vt[6 * TP] = f2bf(b[2]); vt[7 * TP] = f2bf(b[3]);
.LBB0_714:
	v_add_u32_e32 v140, 0xffffc000, v52
	v_lshlrev_b64 v[54:55], 11, v[52:53]
	v_lshlrev_b64 v[60:61], 11, v[140:141]
	s_andn2_b64 vcc, exec, s[74:75]
	v_cndmask_b32_e64 v56, v172, v173, s[10:11]
	v_cndmask_b32_e64 v55, v55, v61, s[10:11]
	v_cndmask_b32_e64 v54, v54, v60, s[10:11]
	s_cbranch_vccnz .LBB0_719
	v_mov_b32_e32 v57, v141
	v_lshl_add_u64 v[60:61], s[18:19], 0, v[56:57]
	v_add_u32_e32 v140, 0xfffffc00, v152
	v_lshl_add_u64 v[60:61], v[60:61], 0, v[54:55]
	v_lshl_add_u64 v[60:61], v[140:141], 2, v[60:61]
	global_store_dwordx4 v[60:61], v[44:47], off
	global_store_dwordx4 v[60:61], v[40:43], off offset:16
	s_and_saveexec_b64 s[74:75], s[8:9]
	s_cbranch_execz .LBB0_717
	v_lshrrev_b32_e32 v53, 7, v140
	v_add_u32_e32 v60, s59, v53
	v_ashrrev_i32_e32 v61, 31, v60
	v_lshlrev_b64 v[60:61], 20, v[60:61]
	v_lshl_add_u64 v[60:61], v[142:143], 0, v[60:61]
	v_lshlrev_b32_e32 v140, 1, v58
	v_lshl_add_u64 v[60:61], v[60:61], 0, v[140:141]
	v_lshrrev_b32_e32 v62, 6, v180
	v_mul_u32_u24_e32 v62, 0x600, v62
	v_add_u32_e32 v62, 0x20000, v62
	v_and_b32_e32 v63, 15, v180
	v_lshl_add_u32 v63, v63, 1, v62
	v_bfe_u32 v140, v180, 4, 2
	v_lshl_add_u32 v63, v140, 8, v63
	v_cvt_pk_bf16_f32 v44, v44, s0
	v_cvt_pk_bf16_f32 v45, v45, s0
	v_cvt_pk_bf16_f32 v46, v46, s0
	v_cvt_pk_bf16_f32 v47, v47, s0
	v_cvt_pk_bf16_f32 v40, v40, s0
	v_cvt_pk_bf16_f32 v41, v41, s0
	v_cvt_pk_bf16_f32 v42, v42, s0
	v_cvt_pk_bf16_f32 v43, v43, s0
	s_nop 0
	ds_write_b16 v63, v44 offset:0
	ds_write_b16 v63, v45 offset:32
	ds_write_b16 v63, v46 offset:64
	ds_write_b16 v63, v47 offset:96
	ds_write_b16 v63, v40 offset:128
	ds_write_b16 v63, v41 offset:160
	ds_write_b16 v63, v42 offset:192
	ds_write_b16 v63, v43 offset:224
	v_and_b32_e32 v140, 63, v180
	v_lshl_add_u32 v62, v140, 4, v62
	v_lshrrev_b32_e32 v63, 1, v140
	s_waitcnt lgkmcnt(0)
	ds_read_b128 v[40:43], v62
	v_lshrrev_b32_e32 v44, 4, v140
	v_lshlrev_b32_e32 v44, 3, v44
	v_sub_u32_e32 v63, v63, v44
	v_lshlrev_b32_e32 v63, 13, v63
	v_and_b32_e32 v44, 1, v140
	v_lshl_add_u32 v63, v44, 4, v63
	v_and_b32_e32 v44, 15, v140
	v_lshlrev_b32_e32 v44, 1, v44
	v_sub_u32_e32 v63, v63, v44
	v_add_co_u32_e32 v60, vcc, v63, v60
	s_nop 1
	v_addc_co_u32_e32 v61, vcc, 0, v61, vcc
	s_waitcnt lgkmcnt(0)
	global_store_dwordx4 v[60:61], v[40:43], off

; __device__ __forceinline__ bf16_t f2bf(float f) { return (bf16_t)(pk2(f, 0.f) & 0xffffu); }
;     __device__ __forceinline__ float* out() const { return (float*)ptr(36); }
;     __device__ __forceinline__ void operator()(const f32x4 (&acc)[2][2][4][2], const Unit& u, int wr, int wc, int fr, int fq) const {
;     ...
;                         if (pn < 6) {
;                             const int vc = c - 1024;
;                             float* vo = smp ? out + O_VS + (size_t)(row - MPR) * 512 + vc : out + O_VP + (size_t)row * 512 + vc;
;                             *(f32x4*)vo = a; *(f32x4*)(vo + 4) = b;
;                             if (!smp) {
;                                 const int bb = row >> 12, t = row & (TP - 1), hh = vc >> 7, dd = vc & 127;
;                                 bf16_t* vt = VT + ((size_t)(bb * 4 + hh) * 128 + dd) * TP + t;
;                                 vt[0] = f2bf(a[0]); vt[TP] = f2bf(a[1]); vt[2 * TP] = f2bf(a[2]); vt[3 * TP] = f2bf(a[3]);
;                                 vt[4 * TP] = f2bf(b[0]); vt[5 * TP] = f2bf(b[1]); vt[6 * TP] = f2bf(b[2]); vt[7 * TP] = f2bf(b[3]);
.LBB0_727:
	v_mov_b32_e32 v57, v141
	v_lshl_add_u64 v[48:49], s[18:19], 0, v[56:57]
	v_add_u32_e32 v140, 0xfffffc80, v152
	v_lshl_add_u64 v[48:49], v[48:49], 0, v[54:55]
	v_lshl_add_u64 v[48:49], v[140:141], 2, v[48:49]
	global_store_dwordx4 v[48:49], v[36:39], off
	global_store_dwordx4 v[48:49], v[32:35], off offset:16
	s_and_saveexec_b64 s[12:13], s[8:9]
	s_cbranch_execz .LBB0_729
	v_lshrrev_b32_e32 v48, 7, v140
	v_add_u32_e32 v48, s59, v48
	v_ashrrev_i32_e32 v49, 31, v48
	v_lshlrev_b64 v[48:49], 20, v[48:49]
	v_lshl_add_u64 v[48:49], v[142:143], 0, v[48:49]
	v_lshlrev_b32_e32 v140, 1, v58
	v_lshl_add_u64 v[48:49], v[48:49], 0, v[140:141]
	v_lshrrev_b32_e32 v50, 6, v180
	v_mul_u32_u24_e32 v50, 0x600, v50
	v_add_u32_e32 v50, 0x20000, v50
	v_and_b32_e32 v51, 15, v180
	v_lshl_add_u32 v51, v51, 1, v50
	v_bfe_u32 v140, v180, 4, 2
	v_lshl_add_u32 v51, v140, 8, v51
	v_cvt_pk_bf16_f32 v36, v36, s0
	v_cvt_pk_bf16_f32 v37, v37, s0
	v_cvt_pk_bf16_f32 v38, v38, s0
	v_cvt_pk_bf16_f32 v39, v39, s0
	v_cvt_pk_bf16_f32 v32, v32, s0
	v_cvt_pk_bf16_f32 v33, v33, s0
	v_cvt_pk_bf16_f32 v34, v34, s0
	v_cvt_pk_bf16_f32 v35, v35, s0
	s_nop 0
	ds_write_b16 v51, v36 offset:0
	ds_write_b16 v51, v37 offset:32
	ds_write_b16 v51, v38 offset:64
	ds_write_b16 v51, v39 offset:96
	ds_write_b16 v51, v32 offset:128
	ds_write_b16 v51, v33 offset:160
	ds_write_b16 v51, v34 offset:192
	ds_write_b16 v51, v35 offset:224
	v_and_b32_e32 v140, 63, v180
	v_lshl_add_u32 v50, v140, 4, v50
	v_lshrrev_b32_e32 v51, 1, v140
	s_waitcnt lgkmcnt(0)
	ds_read_b128 v[32:35], v50
	v_lshrrev_b32_e32 v36, 4, v140
	v_lshlrev_b32_e32 v36, 3, v36
	v_sub_u32_e32 v51, v51, v36
	v_lshlrev_b32_e32 v51, 13, v51
	v_and_b32_e32 v36, 1, v140
	v_lshl_add_u32 v51, v36, 4, v51
	v_and_b32_e32 v36, 15, v140
	v_lshlrev_b32_e32 v36, 1, v36
	v_sub_u32_e32 v51, v51, v36
	v_add_co_u32_e32 v48, vcc, v51, v48
	s_nop 1
	v_addc_co_u32_e32 v49, vcc, 0, v49, vcc
	s_waitcnt lgkmcnt(0)
	global_store_dwordx4 v[48:49], v[32:35], off

; __device__ __forceinline__ bf16_t f2bf(float f) { return (bf16_t)(pk2(f, 0.f) & 0xffffu); }
;     __device__ __forceinline__ float* out() const { return (float*)ptr(36); }
;     __device__ __forceinline__ void operator()(const f32x4 (&acc)[2][2][4][2], const Unit& u, int wr, int wc, int fr, int fq) const {
;     ...
;                         if (pn < 6) {
;                             const int vc = c - 1024;
;                             float* vo = smp ? out + O_VS + (size_t)(row - MPR) * 512 + vc : out + O_VP + (size_t)row * 512 + vc;
;                             *(f32x4*)vo = a; *(f32x4*)(vo + 4) = b;
;                             if (!smp) {
;                                 const int bb = row >> 12, t = row & (TP - 1), hh = vc >> 7, dd = vc & 127;
;                                 bf16_t* vt = VT + ((size_t)(bb * 4 + hh) * 128 + dd) * TP + t;
;                                 vt[0] = f2bf(a[0]); vt[TP] = f2bf(a[1]); vt[2 * TP] = f2bf(a[2]); vt[3 * TP] = f2bf(a[3]);
;                                 vt[4 * TP] = f2bf(b[0]); vt[5 * TP] = f2bf(b[1]); vt[6 * TP] = f2bf(b[2]); vt[7 * TP] = f2bf(b[3]);
.LBB0_750:
	v_add_u32_e32 v140, 0xffffc000, v36
	v_lshlrev_b64 v[38:39], 11, v[36:37]
	v_lshlrev_b64 v[44:45], 11, v[140:141]
	s_andn2_b64 vcc, exec, s[74:75]
	v_cndmask_b32_e64 v40, v172, v173, s[10:11]
	v_cndmask_b32_e64 v39, v39, v45, s[10:11]
	v_cndmask_b32_e64 v38, v38, v44, s[10:11]
	s_cbranch_vccnz .LBB0_755
	v_mov_b32_e32 v41, v141
	v_lshl_add_u64 v[44:45], s[18:19], 0, v[40:41]
	v_add_u32_e32 v140, 0xfffffc00, v152
	v_lshl_add_u64 v[44:45], v[44:45], 0, v[38:39]
	v_lshl_add_u64 v[44:45], v[140:141], 2, v[44:45]
	global_store_dwordx4 v[44:45], v[28:31], off
	global_store_dwordx4 v[44:45], v[24:27], off offset:16
	s_and_saveexec_b64 s[74:75], s[8:9]
	s_cbranch_execz .LBB0_753
	v_lshrrev_b32_e32 v37, 7, v140
	v_add_u32_e32 v44, s59, v37
	v_ashrrev_i32_e32 v45, 31, v44
	v_lshlrev_b64 v[44:45], 20, v[44:45]
	v_lshl_add_u64 v[44:45], v[142:143], 0, v[44:45]
	v_lshlrev_b32_e32 v140, 1, v42
	v_lshl_add_u64 v[44:45], v[44:45], 0, v[140:141]
	v_lshrrev_b32_e32 v46, 6, v180
	v_mul_u32_u24_e32 v46, 0x600, v46
	v_add_u32_e32 v46, 0x20000, v46
	v_and_b32_e32 v47, 15, v180
	v_lshl_add_u32 v47, v47, 1, v46
	v_bfe_u32 v140, v180, 4, 2
	v_lshl_add_u32 v47, v140, 8, v47
	v_cvt_pk_bf16_f32 v28, v28, s0
	v_cvt_pk_bf16_f32 v29, v29, s0
	v_cvt_pk_bf16_f32 v30, v30, s0
	v_cvt_pk_bf16_f32 v31, v31, s0
	v_cvt_pk_bf16_f32 v24, v24, s0
	v_cvt_pk_bf16_f32 v25, v25, s0
	v_cvt_pk_bf16_f32 v26, v26, s0
	v_cvt_pk_bf16_f32 v27, v27, s0
	s_nop 0
	ds_write_b16 v47, v28 offset:0
	ds_write_b16 v47, v29 offset:32
	ds_write_b16 v47, v30 offset:64
	ds_write_b16 v47, v31 offset:96
	ds_write_b16 v47, v24 offset:128
	ds_write_b16 v47, v25 offset:160
	ds_write_b16 v47, v26 offset:192
	ds_write_b16 v47, v27 offset:224
	v_and_b32_e32 v140, 63, v180
	v_lshl_add_u32 v46, v140, 4, v46
	v_lshrrev_b32_e32 v47, 1, v140
	s_waitcnt lgkmcnt(0)
	ds_read_b128 v[24:27], v46
	v_lshrrev_b32_e32 v28, 4, v140
	v_lshlrev_b32_e32 v28, 3, v28
	v_sub_u32_e32 v47, v47, v28
	v_lshlrev_b32_e32 v47, 13, v47
	v_and_b32_e32 v28, 1, v140
	v_lshl_add_u32 v47, v28, 4, v47
	v_and_b32_e32 v28, 15, v140
	v_lshlrev_b32_e32 v28, 1, v28
	v_sub_u32_e32 v47, v47, v28
	v_add_co_u32_e32 v44, vcc, v47, v44
	s_nop 1
	v_addc_co_u32_e32 v45, vcc, 0, v45, vcc
	s_waitcnt lgkmcnt(0)
	global_store_dwordx4 v[44:45], v[24:27], off

; __device__ __forceinline__ bf16_t f2bf(float f) { return (bf16_t)(pk2(f, 0.f) & 0xffffu); }
;     __device__ __forceinline__ float* out() const { return (float*)ptr(36); }
;     __device__ __forceinline__ void operator()(const f32x4 (&acc)[2][2][4][2], const Unit& u, int wr, int wc, int fr, int fq) const {
;     ...
;                         if (pn < 6) {
;                             const int vc = c - 1024;
;                             float* vo = smp ? out + O_VS + (size_t)(row - MPR) * 512 + vc : out + O_VP + (size_t)row * 512 + vc;
;                             *(f32x4*)vo = a; *(f32x4*)(vo + 4) = b;
;                             if (!smp) {
;                                 const int bb = row >> 12, t = row & (TP - 1), hh = vc >> 7, dd = vc & 127;
;                                 bf16_t* vt = VT + ((size_t)(bb * 4 + hh) * 128 + dd) * TP + t;
;                                 vt[0] = f2bf(a[0]); vt[TP] = f2bf(a[1]); vt[2 * TP] = f2bf(a[2]); vt[3 * TP] = f2bf(a[3]);
;                                 vt[4 * TP] = f2bf(b[0]); vt[5 * TP] = f2bf(b[1]); vt[6 * TP] = f2bf(b[2]); vt[7 * TP] = f2bf(b[3]);
.LBB0_763:
	v_mov_b32_e32 v41, v141
	v_lshl_add_u64 v[32:33], s[18:19], 0, v[40:41]
	v_add_u32_e32 v140, 0xfffffc80, v152
	v_lshl_add_u64 v[32:33], v[32:33], 0, v[38:39]
	v_lshl_add_u64 v[32:33], v[140:141], 2, v[32:33]
	global_store_dwordx4 v[32:33], v[20:23], off
	global_store_dwordx4 v[32:33], v[16:19], off offset:16
	s_and_saveexec_b64 s[12:13], s[8:9]
	s_cbranch_execz .LBB0_765
	v_lshrrev_b32_e32 v32, 7, v140
	v_add_u32_e32 v32, s59, v32
	v_ashrrev_i32_e32 v33, 31, v32
	v_lshlrev_b64 v[32:33], 20, v[32:33]
	v_lshl_add_u64 v[32:33], v[142:143], 0, v[32:33]
	v_lshlrev_b32_e32 v140, 1, v42
	v_lshl_add_u64 v[32:33], v[32:33], 0, v[140:141]
	v_lshrrev_b32_e32 v34, 6, v180
	v_mul_u32_u24_e32 v34, 0x600, v34
	v_add_u32_e32 v34, 0x20000, v34
	v_and_b32_e32 v35, 15, v180
	v_lshl_add_u32 v35, v35, 1, v34
	v_bfe_u32 v140, v180, 4, 2
	v_lshl_add_u32 v35, v140, 8, v35
	v_cvt_pk_bf16_f32 v20, v20, s0
	v_cvt_pk_bf16_f32 v21, v21, s0
	v_cvt_pk_bf16_f32 v22, v22, s0
	v_cvt_pk_bf16_f32 v23, v23, s0
	v_cvt_pk_bf16_f32 v16, v16, s0
	v_cvt_pk_bf16_f32 v17, v17, s0
	v_cvt_pk_bf16_f32 v18, v18, s0
	v_cvt_pk_bf16_f32 v19, v19, s0
	s_nop 0
	ds_write_b16 v35, v20 offset:0
	ds_write_b16 v35, v21 offset:32
	ds_write_b16 v35, v22 offset:64
	ds_write_b16 v35, v23 offset:96
	ds_write_b16 v35, v16 offset:128
	ds_write_b16 v35, v17 offset:160
	ds_write_b16 v35, v18 offset:192
	ds_write_b16 v35, v19 offset:224
	v_and_b32_e32 v140, 63, v180
	v_lshl_add_u32 v34, v140, 4, v34
	v_lshrrev_b32_e32 v35, 1, v140
	s_waitcnt lgkmcnt(0)
	ds_read_b128 v[16:19], v34
	v_lshrrev_b32_e32 v20, 4, v140
	v_lshlrev_b32_e32 v20, 3, v20
	v_sub_u32_e32 v35, v35, v20
	v_lshlrev_b32_e32 v35, 13, v35
	v_and_b32_e32 v20, 1, v140
	v_lshl_add_u32 v35, v20, 4, v35
	v_and_b32_e32 v20, 15, v140
	v_lshlrev_b32_e32 v20, 1, v20
	v_sub_u32_e32 v35, v35, v20
	v_add_co_u32_e32 v32, vcc, v35, v32
	s_nop 1
	v_addc_co_u32_e32 v33, vcc, 0, v33, vcc
	s_waitcnt lgkmcnt(0)
	global_store_dwordx4 v[32:33], v[16:19], off

; __device__ __forceinline__ bf16_t f2bf(float f) { return (bf16_t)(pk2(f, 0.f) & 0xffffu); }
;     __device__ __forceinline__ float* out() const { return (float*)ptr(36); }
;     __device__ __forceinline__ void operator()(const f32x4 (&acc)[2][2][4][2], const Unit& u, int wr, int wc, int fr, int fq) const {
;     ...
;                         if (pn < 6) {
;                             const int vc = c - 1024;
;                             float* vo = smp ? out + O_VS + (size_t)(row - MPR) * 512 + vc : out + O_VP + (size_t)row * 512 + vc;
;                             *(f32x4*)vo = a; *(f32x4*)(vo + 4) = b;
;                             if (!smp) {
;                                 const int bb = row >> 12, t = row & (TP - 1), hh = vc >> 7, dd = vc & 127;
;                                 bf16_t* vt = VT + ((size_t)(bb * 4 + hh) * 128 + dd) * TP + t;
;                                 vt[0] = f2bf(a[0]); vt[TP] = f2bf(a[1]); vt[2 * TP] = f2bf(a[2]); vt[3 * TP] = f2bf(a[3]);
;                                 vt[4 * TP] = f2bf(b[0]); vt[5 * TP] = f2bf(b[1]); vt[6 * TP] = f2bf(b[2]); vt[7 * TP] = f2bf(b[3]);
.LBB0_786:
	v_add_u32_e32 v140, 0xffffc000, v20
	v_lshlrev_b64 v[22:23], 11, v[20:21]
	v_lshlrev_b64 v[28:29], 11, v[140:141]
	s_andn2_b64 vcc, exec, s[76:77]
	v_cndmask_b32_e64 v24, v172, v173, s[10:11]
	v_cndmask_b32_e64 v23, v23, v29, s[10:11]
	v_cndmask_b32_e64 v22, v22, v28, s[10:11]
	s_cbranch_vccnz .LBB0_791
	v_mov_b32_e32 v25, v141
	v_lshl_add_u64 v[28:29], s[18:19], 0, v[24:25]
	v_add_u32_e32 v140, 0xfffffc00, v152
	v_lshl_add_u64 v[28:29], v[28:29], 0, v[22:23]
	v_lshl_add_u64 v[28:29], v[140:141], 2, v[28:29]
	global_store_dwordx4 v[28:29], v[12:15], off
	global_store_dwordx4 v[28:29], v[8:11], off offset:16
	s_and_saveexec_b64 s[68:69], s[8:9]
	s_cbranch_execz .LBB0_789
	v_lshrrev_b32_e32 v21, 7, v140
	v_add_u32_e32 v28, s59, v21
	v_ashrrev_i32_e32 v29, 31, v28
	v_lshlrev_b64 v[28:29], 20, v[28:29]
	v_lshl_add_u64 v[28:29], v[142:143], 0, v[28:29]
	v_lshlrev_b32_e32 v140, 1, v26
	v_lshl_add_u64 v[28:29], v[28:29], 0, v[140:141]
	v_lshrrev_b32_e32 v30, 6, v180
	v_mul_u32_u24_e32 v30, 0x600, v30
	v_add_u32_e32 v30, 0x20000, v30
	v_and_b32_e32 v31, 15, v180
	v_lshl_add_u32 v31, v31, 1, v30
	v_bfe_u32 v140, v180, 4, 2
	v_lshl_add_u32 v31, v140, 8, v31
	v_cvt_pk_bf16_f32 v12, v12, s0
	v_cvt_pk_bf16_f32 v13, v13, s0
	v_cvt_pk_bf16_f32 v14, v14, s0
	v_cvt_pk_bf16_f32 v15, v15, s0
	v_cvt_pk_bf16_f32 v8, v8, s0
	v_cvt_pk_bf16_f32 v9, v9, s0
	v_cvt_pk_bf16_f32 v10, v10, s0
	v_cvt_pk_bf16_f32 v11, v11, s0
	s_nop 0
	ds_write_b16 v31, v12 offset:0
	ds_write_b16 v31, v13 offset:32
	ds_write_b16 v31, v14 offset:64
	ds_write_b16 v31, v15 offset:96
	ds_write_b16 v31, v8 offset:128
	ds_write_b16 v31, v9 offset:160
	ds_write_b16 v31, v10 offset:192
	ds_write_b16 v31, v11 offset:224
	v_and_b32_e32 v140, 63, v180
	v_lshl_add_u32 v30, v140, 4, v30
	v_lshrrev_b32_e32 v31, 1, v140
	s_waitcnt lgkmcnt(0)
	ds_read_b128 v[8:11], v30
	v_lshrrev_b32_e32 v12, 4, v140
	v_lshlrev_b32_e32 v12, 3, v12
	v_sub_u32_e32 v31, v31, v12
	v_lshlrev_b32_e32 v31, 13, v31
	v_and_b32_e32 v12, 1, v140
	v_lshl_add_u32 v31, v12, 4, v31
	v_and_b32_e32 v12, 15, v140
	v_lshlrev_b32_e32 v12, 1, v12
	v_sub_u32_e32 v31, v31, v12
	v_add_co_u32_e32 v28, vcc, v31, v28
	s_nop 1
	v_addc_co_u32_e32 v29, vcc, 0, v29, vcc
	s_waitcnt lgkmcnt(0)
	global_store_dwordx4 v[28:29], v[8:11], off

; __device__ __forceinline__ bf16_t f2bf(float f) { return (bf16_t)(pk2(f, 0.f) & 0xffffu); }
;     __device__ __forceinline__ float* out() const { return (float*)ptr(36); }
;     __device__ __forceinline__ void operator()(const f32x4 (&acc)[2][2][4][2], const Unit& u, int wr, int wc, int fr, int fq) const {
;     ...
;                         if (pn < 6) {
;                             const int vc = c - 1024;
;                             float* vo = smp ? out + O_VS + (size_t)(row - MPR) * 512 + vc : out + O_VP + (size_t)row * 512 + vc;
;                             *(f32x4*)vo = a; *(f32x4*)(vo + 4) = b;
;                             if (!smp) {
;                                 const int bb = row >> 12, t = row & (TP - 1), hh = vc >> 7, dd = vc & 127;
;                                 bf16_t* vt = VT + ((size_t)(bb * 4 + hh) * 128 + dd) * TP + t;
;                                 vt[0] = f2bf(a[0]); vt[TP] = f2bf(a[1]); vt[2 * TP] = f2bf(a[2]); vt[3 * TP] = f2bf(a[3]);
;                                 vt[4 * TP] = f2bf(b[0]); vt[5 * TP] = f2bf(b[1]); vt[6 * TP] = f2bf(b[2]); vt[7 * TP] = f2bf(b[3]);
.LBB0_799:
	v_mov_b32_e32 v25, v141
	v_lshl_add_u64 v[16:17], s[18:19], 0, v[24:25]
	v_add_u32_e32 v140, 0xfffffc80, v152
	v_lshl_add_u64 v[16:17], v[16:17], 0, v[22:23]
	v_lshl_add_u64 v[16:17], v[140:141], 2, v[16:17]
	global_store_dwordx4 v[16:17], v[4:7], off
	global_store_dwordx4 v[16:17], v[0:3], off offset:16
	s_and_saveexec_b64 s[6:7], s[8:9]
	s_cbranch_execz .LBB0_801
	v_lshrrev_b32_e32 v16, 7, v140
	v_add_u32_e32 v16, s59, v16
	v_ashrrev_i32_e32 v17, 31, v16
	v_lshlrev_b64 v[16:17], 20, v[16:17]
	v_lshl_add_u64 v[16:17], v[142:143], 0, v[16:17]
	v_lshlrev_b32_e32 v140, 1, v26
	v_lshl_add_u64 v[16:17], v[16:17], 0, v[140:141]
	v_lshrrev_b32_e32 v18, 6, v180
	v_mul_u32_u24_e32 v18, 0x600, v18
	v_add_u32_e32 v18, 0x20000, v18
	v_and_b32_e32 v19, 15, v180
	v_lshl_add_u32 v19, v19, 1, v18
	v_bfe_u32 v140, v180, 4, 2
	v_lshl_add_u32 v19, v140, 8, v19
	v_cvt_pk_bf16_f32 v4, v4, s0
	v_cvt_pk_bf16_f32 v5, v5, s0
	v_cvt_pk_bf16_f32 v6, v6, s0
	v_cvt_pk_bf16_f32 v7, v7, s0
	v_cvt_pk_bf16_f32 v0, v0, s0
	v_cvt_pk_bf16_f32 v1, v1, s0
	v_cvt_pk_bf16_f32 v2, v2, s0
	v_cvt_pk_bf16_f32 v3, v3, s0
	s_nop 0
	ds_write_b16 v19, v4 offset:0
	ds_write_b16 v19, v5 offset:32
	ds_write_b16 v19, v6 offset:64
	ds_write_b16 v19, v7 offset:96
	ds_write_b16 v19, v0 offset:128
	ds_write_b16 v19, v1 offset:160
	ds_write_b16 v19, v2 offset:192
	ds_write_b16 v19, v3 offset:224
	v_and_b32_e32 v140, 63, v180
	v_lshl_add_u32 v18, v140, 4, v18
	v_lshrrev_b32_e32 v19, 1, v140
	s_waitcnt lgkmcnt(0)
	ds_read_b128 v[0:3], v18
	v_lshrrev_b32_e32 v4, 4, v140
	v_lshlrev_b32_e32 v4, 3, v4
	v_sub_u32_e32 v19, v19, v4
	v_lshlrev_b32_e32 v19, 13, v19
	v_and_b32_e32 v4, 1, v140
	v_lshl_add_u32 v19, v4, 4, v19
	v_and_b32_e32 v4, 15, v140
	v_lshlrev_b32_e32 v4, 1, v4
	v_sub_u32_e32 v19, v19, v4
	v_add_co_u32_e32 v16, vcc, v19, v16
	s_nop 1
	v_addc_co_u32_e32 v17, vcc, 0, v17, vcc
	s_waitcnt lgkmcnt(0)
	global_store_dwordx4 v[16:17], v[0:3], off
